# v08 + grid barrier: XCD leaders wait on the monotonic cross-XCD arrival counter (TOP) instead of the release generation word (one fabric hop less per barrier)
# baseline (speedup 1.0000x reference)
.LBB0_216:
	s_or_b64 exec, exec, s[8:9]
	s_waitcnt vmcnt(0)
	v_readfirstlane_b32 s4, v2
	v_cvt_f32_u32_e32 v2, v0
	v_sub_u32_e32 v3, 0, v0
	v_add_u32_e32 v1, s4, v1
	v_readlane_b32 s4, v242, 44
	v_rcp_iflag_f32_e32 v2, v2
	v_readlane_b32 s5, v242, 45
	s_mov_b64 s[8:9], -1
	v_mul_f32_e32 v2, 0x4f7ffffe, v2
	v_cvt_u32_f32_e32 v2, v2
	v_mul_lo_u32 v3, v3, v2
	v_mul_hi_u32 v3, v2, v3
	v_add_u32_e32 v2, v2, v3
	v_mul_hi_u32 v2, v1, v2
	v_mul_lo_u32 v3, v2, v0
	v_sub_u32_e32 v3, v1, v3
	v_cmp_ge_u32_e32 vcc, v3, v0
	v_add_u32_e32 v4, 1, v2
	v_add_u32_e32 v1, 1, v1
	v_cndmask_b32_e32 v2, v2, v4, vcc
	v_sub_u32_e32 v4, v3, v0
	v_cndmask_b32_e32 v3, v3, v4, vcc
	v_cmp_ge_u32_e32 vcc, v3, v0
	v_add_u32_e32 v3, 1, v2
	s_nop 0
	v_cndmask_b32_e32 v2, v2, v3, vcc
	v_mul_lo_u32 v3, v0, v2
	v_add_u32_e32 v0, v3, v0
	v_cmp_ne_u32_e32 vcc, v1, v0
	v_mov_b32_e32 v3, v0
	v_mov_b64_e32 v[0:1], s[4:5]
	s_and_saveexec_b64 s[4:5], vcc
	s_cbranch_execz .LBB0_228
	v_readlane_b32 s8, v242, 42
	v_readlane_b32 s9, v242, 43
	s_mov_b64 s[38:39], 0
	s_nop 3
	global_load_dword v0, v173, s[8:9] sc1
	s_waitcnt vmcnt(0)
	v_sub_u32_e32 v0, v0, v3
	v_cmp_gt_i32_e32 vcc, 0, v0
	s_and_saveexec_b64 s[8:9], vcc
	s_cbranch_execz .LBB0_227
	s_mov_b32 s11, 1
	s_branch .LBB0_220

.LBB0_222:
	v_readlane_b32 s42, v242, 42
	v_readlane_b32 s43, v242, 43
	s_add_i32 s11, s11, 1
	s_mov_b64 s[44:45], -1
	s_nop 2
	global_load_dword v0, v173, s[42:43] sc1
	s_waitcnt vmcnt(0)
	v_sub_u32_e32 v0, v0, v3
	v_cmp_le_i32_e32 vcc, 0, v0
	s_orn2_b64 s[42:43], vcc, exec
	s_branch .LBB0_219

.LBB0_756:
	s_or_b64 exec, exec, s[8:9]
	s_waitcnt vmcnt(0)
	v_readfirstlane_b32 s4, v2
	v_cvt_f32_u32_e32 v2, v0
	v_sub_u32_e32 v3, 0, v0
	v_add_u32_e32 v1, s4, v1
	v_readlane_b32 s4, v242, 44
	v_rcp_iflag_f32_e32 v2, v2
	v_readlane_b32 s5, v242, 45
	s_mov_b64 s[8:9], -1
	v_mul_f32_e32 v2, 0x4f7ffffe, v2
	v_cvt_u32_f32_e32 v2, v2
	v_mul_lo_u32 v3, v3, v2
	v_mul_hi_u32 v3, v2, v3
	v_add_u32_e32 v2, v2, v3
	v_mul_hi_u32 v2, v1, v2
	v_mul_lo_u32 v3, v2, v0
	v_sub_u32_e32 v3, v1, v3
	v_cmp_ge_u32_e32 vcc, v3, v0
	v_add_u32_e32 v4, 1, v2
	v_add_u32_e32 v1, 1, v1
	v_cndmask_b32_e32 v2, v2, v4, vcc
	v_sub_u32_e32 v4, v3, v0
	v_cndmask_b32_e32 v3, v3, v4, vcc
	v_cmp_ge_u32_e32 vcc, v3, v0
	v_add_u32_e32 v3, 1, v2
	s_nop 0
	v_cndmask_b32_e32 v2, v2, v3, vcc
	v_mul_lo_u32 v3, v0, v2
	v_add_u32_e32 v0, v3, v0
	v_cmp_ne_u32_e32 vcc, v1, v0
	v_mov_b32_e32 v3, v0
	v_mov_b64_e32 v[0:1], s[4:5]
	s_and_saveexec_b64 s[4:5], vcc
	s_cbranch_execz .LBB0_768
	v_readlane_b32 s8, v242, 42
	v_readlane_b32 s9, v242, 43
	s_mov_b64 s[28:29], 0
	s_nop 3
	global_load_dword v0, v173, s[8:9] sc1
	s_waitcnt vmcnt(0)
	v_sub_u32_e32 v0, v0, v3
	v_cmp_gt_i32_e32 vcc, 0, v0
	s_and_saveexec_b64 s[8:9], vcc
	s_cbranch_execz .LBB0_767
	s_mov_b32 s11, 1
	s_branch .LBB0_760

.LBB0_762:
	v_readlane_b32 s40, v242, 42
	v_readlane_b32 s41, v242, 43
	s_add_i32 s11, s11, 1
	s_mov_b64 s[42:43], -1
	s_nop 2
	global_load_dword v0, v173, s[40:41] sc1
	s_waitcnt vmcnt(0)
	v_sub_u32_e32 v0, v0, v3
	v_cmp_le_i32_e32 vcc, 0, v0
	s_orn2_b64 s[40:41], vcc, exec
	s_branch .LBB0_759

.LBB0_1067:
	s_or_b64 exec, exec, s[8:9]
	s_waitcnt vmcnt(0)
	v_readfirstlane_b32 s4, v2
	v_cvt_f32_u32_e32 v2, v0
	v_sub_u32_e32 v3, 0, v0
	v_add_u32_e32 v1, s4, v1
	v_readlane_b32 s4, v242, 44
	v_rcp_iflag_f32_e32 v2, v2
	v_readlane_b32 s5, v242, 45
	s_mov_b64 s[8:9], -1
	v_mul_f32_e32 v2, 0x4f7ffffe, v2
	v_cvt_u32_f32_e32 v2, v2
	v_mul_lo_u32 v3, v3, v2
	v_mul_hi_u32 v3, v2, v3
	v_add_u32_e32 v2, v2, v3
	v_mul_hi_u32 v2, v1, v2
	v_mul_lo_u32 v3, v2, v0
	v_sub_u32_e32 v3, v1, v3
	v_cmp_ge_u32_e32 vcc, v3, v0
	v_add_u32_e32 v4, 1, v2
	v_add_u32_e32 v1, 1, v1
	v_cndmask_b32_e32 v2, v2, v4, vcc
	v_sub_u32_e32 v4, v3, v0
	v_cndmask_b32_e32 v3, v3, v4, vcc
	v_cmp_ge_u32_e32 vcc, v3, v0
	v_add_u32_e32 v3, 1, v2
	s_nop 0
	v_cndmask_b32_e32 v2, v2, v3, vcc
	v_mul_lo_u32 v3, v0, v2
	v_add_u32_e32 v0, v3, v0
	v_cmp_ne_u32_e32 vcc, v1, v0
	v_mov_b32_e32 v3, v0
	v_mov_b64_e32 v[0:1], s[4:5]
	s_and_saveexec_b64 s[4:5], vcc
	s_cbranch_execz .LBB0_1079
	v_readlane_b32 s8, v242, 42
	v_readlane_b32 s9, v242, 43
	s_mov_b64 s[28:29], 0
	s_nop 3
	global_load_dword v0, v173, s[8:9] sc1
	s_waitcnt vmcnt(0)
	v_sub_u32_e32 v0, v0, v3
	v_cmp_gt_i32_e32 vcc, 0, v0
	s_and_saveexec_b64 s[8:9], vcc
	s_cbranch_execz .LBB0_1078
	s_mov_b32 s26, 1
	s_branch .LBB0_1071

.LBB0_1073:
	v_readlane_b32 s40, v242, 42
	v_readlane_b32 s41, v242, 43
	s_add_i32 s26, s26, 1
	s_mov_b64 s[42:43], -1
	s_nop 2
	global_load_dword v0, v173, s[40:41] sc1
	s_waitcnt vmcnt(0)
	v_sub_u32_e32 v0, v0, v3
	v_cmp_le_i32_e32 vcc, 0, v0
	s_orn2_b64 s[40:41], vcc, exec
	s_branch .LBB0_1070

.LBB0_1124:
	s_or_b64 exec, exec, s[8:9]
	s_waitcnt vmcnt(0)
	v_readfirstlane_b32 s4, v2
	v_cvt_f32_u32_e32 v2, v0
	v_sub_u32_e32 v3, 0, v0
	v_add_u32_e32 v1, s4, v1
	v_readlane_b32 s4, v242, 44
	v_rcp_iflag_f32_e32 v2, v2
	v_readlane_b32 s5, v242, 45
	s_mov_b64 s[8:9], -1
	v_mul_f32_e32 v2, 0x4f7ffffe, v2
	v_cvt_u32_f32_e32 v2, v2
	v_mul_lo_u32 v3, v3, v2
	v_mul_hi_u32 v3, v2, v3
	v_add_u32_e32 v2, v2, v3
	v_mul_hi_u32 v2, v1, v2
	v_mul_lo_u32 v3, v2, v0
	v_sub_u32_e32 v3, v1, v3
	v_cmp_ge_u32_e32 vcc, v3, v0
	v_add_u32_e32 v4, 1, v2
	v_add_u32_e32 v1, 1, v1
	v_cndmask_b32_e32 v2, v2, v4, vcc
	v_sub_u32_e32 v4, v3, v0
	v_cndmask_b32_e32 v3, v3, v4, vcc
	v_cmp_ge_u32_e32 vcc, v3, v0
	v_add_u32_e32 v3, 1, v2
	s_nop 0
	v_cndmask_b32_e32 v2, v2, v3, vcc
	v_mul_lo_u32 v3, v0, v2
	v_add_u32_e32 v0, v3, v0
	v_cmp_ne_u32_e32 vcc, v1, v0
	v_mov_b32_e32 v3, v0
	v_mov_b64_e32 v[0:1], s[4:5]
	s_and_saveexec_b64 s[4:5], vcc
	s_cbranch_execz .LBB0_1136
	v_readlane_b32 s8, v242, 42
	v_readlane_b32 s9, v242, 43
	s_mov_b64 s[38:39], 0
	s_nop 3
	global_load_dword v0, v173, s[8:9] sc1
	s_waitcnt vmcnt(0)
	v_sub_u32_e32 v0, v0, v3
	v_cmp_gt_i32_e32 vcc, 0, v0
	s_and_saveexec_b64 s[8:9], vcc
	s_cbranch_execz .LBB0_1135
	s_mov_b32 s26, 1
	s_branch .LBB0_1128

.LBB0_1130:
	v_readlane_b32 s42, v242, 42
	v_readlane_b32 s43, v242, 43
	s_add_i32 s26, s26, 1
	s_mov_b64 s[44:45], -1
	s_nop 2
	global_load_dword v0, v173, s[42:43] sc1
	s_waitcnt vmcnt(0)
	v_sub_u32_e32 v0, v0, v3
	v_cmp_le_i32_e32 vcc, 0, v0
	s_orn2_b64 s[42:43], vcc, exec
	s_branch .LBB0_1127

.LBB0_1196:
	s_or_b64 exec, exec, s[8:9]
	s_waitcnt vmcnt(0)
	v_readfirstlane_b32 s4, v2
	v_cvt_f32_u32_e32 v2, v0
	v_sub_u32_e32 v3, 0, v0
	v_add_u32_e32 v1, s4, v1
	v_readlane_b32 s4, v242, 44
	v_rcp_iflag_f32_e32 v2, v2
	v_readlane_b32 s5, v242, 45
	s_mov_b64 s[8:9], -1
	v_mul_f32_e32 v2, 0x4f7ffffe, v2
	v_cvt_u32_f32_e32 v2, v2
	v_mul_lo_u32 v3, v3, v2
	v_mul_hi_u32 v3, v2, v3
	v_add_u32_e32 v2, v2, v3
	v_mul_hi_u32 v2, v1, v2
	v_mul_lo_u32 v3, v2, v0
	v_sub_u32_e32 v3, v1, v3
	v_cmp_ge_u32_e32 vcc, v3, v0
	v_add_u32_e32 v4, 1, v2
	v_add_u32_e32 v1, 1, v1
	v_cndmask_b32_e32 v2, v2, v4, vcc
	v_sub_u32_e32 v4, v3, v0
	v_cndmask_b32_e32 v3, v3, v4, vcc
	v_cmp_ge_u32_e32 vcc, v3, v0
	v_add_u32_e32 v3, 1, v2
	s_nop 0
	v_cndmask_b32_e32 v2, v2, v3, vcc
	v_mul_lo_u32 v3, v0, v2
	v_add_u32_e32 v0, v3, v0
	v_cmp_ne_u32_e32 vcc, v1, v0
	v_mov_b32_e32 v3, v0
	v_mov_b64_e32 v[0:1], s[4:5]
	s_and_saveexec_b64 s[4:5], vcc
	s_cbranch_execz .LBB0_1208
	v_readlane_b32 s8, v242, 42
	v_readlane_b32 s9, v242, 43
	s_mov_b64 s[42:43], 0
	s_nop 3
	global_load_dword v0, v173, s[8:9] sc1
	s_waitcnt vmcnt(0)
	v_sub_u32_e32 v0, v0, v3
	v_cmp_gt_i32_e32 vcc, 0, v0
	s_and_saveexec_b64 s[8:9], vcc
	s_cbranch_execz .LBB0_1207
	s_mov_b32 s26, 1
	s_branch .LBB0_1200

.LBB0_1202:
	v_readlane_b32 s46, v242, 42
	v_readlane_b32 s47, v242, 43
	s_add_i32 s26, s26, 1
	s_mov_b64 s[48:49], -1
	s_nop 2
	global_load_dword v0, v173, s[46:47] sc1
	s_waitcnt vmcnt(0)
	v_sub_u32_e32 v0, v0, v3
	v_cmp_le_i32_e32 vcc, 0, v0
	s_orn2_b64 s[46:47], vcc, exec
	s_branch .LBB0_1199

.LBB0_1382:
	s_or_b64 exec, exec, s[8:9]
	s_waitcnt vmcnt(0)
	v_readfirstlane_b32 s4, v2
	v_cvt_f32_u32_e32 v2, v0
	v_sub_u32_e32 v3, 0, v0
	v_add_u32_e32 v1, s4, v1
	v_readlane_b32 s4, v242, 44
	v_rcp_iflag_f32_e32 v2, v2
	v_readlane_b32 s5, v242, 45
	s_mov_b64 s[8:9], -1
	v_mul_f32_e32 v2, 0x4f7ffffe, v2
	v_cvt_u32_f32_e32 v2, v2
	v_mul_lo_u32 v3, v3, v2
	v_mul_hi_u32 v3, v2, v3
	v_add_u32_e32 v2, v2, v3
	v_mul_hi_u32 v2, v1, v2
	v_mul_lo_u32 v3, v2, v0
	v_sub_u32_e32 v3, v1, v3
	v_cmp_ge_u32_e32 vcc, v3, v0
	v_add_u32_e32 v4, 1, v2
	v_add_u32_e32 v1, 1, v1
	v_cndmask_b32_e32 v2, v2, v4, vcc
	v_sub_u32_e32 v4, v3, v0
	v_cndmask_b32_e32 v3, v3, v4, vcc
	v_cmp_ge_u32_e32 vcc, v3, v0
	v_add_u32_e32 v3, 1, v2
	s_nop 0
	v_cndmask_b32_e32 v2, v2, v3, vcc
	v_mul_lo_u32 v3, v0, v2
	v_add_u32_e32 v0, v3, v0
	v_cmp_ne_u32_e32 vcc, v1, v0
	v_mov_b32_e32 v3, v0
	v_mov_b64_e32 v[0:1], s[4:5]
	s_and_saveexec_b64 s[4:5], vcc
	s_cbranch_execz .LBB0_1394
	v_readlane_b32 s8, v242, 42
	v_readlane_b32 s9, v242, 43
	s_mov_b64 s[40:41], 0
	s_nop 3
	global_load_dword v0, v173, s[8:9] sc1
	s_waitcnt vmcnt(0)
	v_sub_u32_e32 v0, v0, v3
	v_cmp_gt_i32_e32 vcc, 0, v0
	s_and_saveexec_b64 s[8:9], vcc
	s_cbranch_execz .LBB0_1393
	s_mov_b32 s26, 1
	s_branch .LBB0_1386

.LBB0_1388:
	v_readlane_b32 s44, v242, 42
	v_readlane_b32 s45, v242, 43
	s_add_i32 s26, s26, 1
	s_mov_b64 s[46:47], -1
	s_nop 2
	global_load_dword v0, v173, s[44:45] sc1
	s_waitcnt vmcnt(0)
	v_sub_u32_e32 v0, v0, v3
	v_cmp_le_i32_e32 vcc, 0, v0
	s_orn2_b64 s[44:45], vcc, exec
	s_branch .LBB0_1385
